# combination: z_p epilogue with all read-backs in flight, phase-4 weight transposes with all loads in flight, hand-written box filter, on top of the ones-column mask removal and baseline K-loop byte ph
# speedup vs baseline: 1.0006x; 1.0006x over previous
; #define LAS __attribute__((address_space(3)))
; __device__ __forceinline__ int opaque_tid() { int t = (int)threadIdx.x; asm volatile("" : "+v"(t)); return t; }
; __device__ __forceinline__ unsigned cvt_pk_bf16(float lo, float hi) { unsigned r; asm volatile("v_cvt_pk_bf16_f32 %0, %1, %2" : "=v"(r) : "v"(lo), "v"(hi)); return r; }
; __device__ __forceinline__ void transpose_tile(const float* src, int ld_src, int k0, int c0, bf16_t* dst, int ld_dst, int n0, LAS float* T) {
;     const int tid = opaque_tid();
; #pragma unroll
;     for (int i = 0; i < 2; ++i) { const int r = (tid >> 4) + i * 32, c4 = (tid & 15) * 4;
;         const f32x4 v = __builtin_nontemporal_load((const f32x4*)(src + (size_t)(k0 + r) * ld_src + c0 + c4));
;         T[r * 65 + c4] = v[0]; T[r * 65 + c4 + 1] = v[1]; T[r * 65 + c4 + 2] = v[2]; T[r * 65 + c4 + 3] = v[3]; }
;     __syncthreads();
;     { const int n = tid >> 3, kc = (tid & 7) * 8; float f[8];
; #pragma unroll
;         for (int j = 0; j < 8; ++j) f[j] = T[(kc + j) * 65 + n];
;         u32x4 w; w.x = cvt_pk_bf16(f[0], f[1]); w.y = cvt_pk_bf16(f[2], f[3]); w.z = cvt_pk_bf16(f[4], f[5]); w.w = cvt_pk_bf16(f[6], f[7]);
;         *(u32x4*)(dst + (size_t)(n0 + n) * ld_dst + k0 + kc) = w; }
;     __syncthreads();
; }
; __device__ __forceinline__ void run_phase(const Params& p, LAS unsigned char* lds, int ph) {
;     ...
;         if (j < 2) {
;             LAS float* T = (LAS float*)lds; const int w128 = pmt * 2 + j;
;             for (int job = w128; job < 640; job += 128) {
;                 if (job < 256) { const int kt = job & 15, ntile = job >> 4; transpose_tile(p.branch_m_w, 1024, kt * 64, ntile * 64, (bf16_t*)(p.ws + OFF_WMT), 1024, ntile * 64, T); }
;                 else if (job < 512) { const int j2 = job - 256; const int kt = j2 & 15, ntile = j2 >> 4; transpose_tile(p.out_w, 1024, kt * 64, ntile * 64, (bf16_t*)(p.ws + OFF_WOT), 1024, ntile * 64, T); }
;                 else { const int j2 = job - 512; const int kt = j2 & 7, ntile = j2 >> 3; transpose_tile(p.branch_p_w, 1024, kt * 64, ntile * 64, (bf16_t*)(p.ws + OFF_WPT), 512, ntile * 64, T); }
;             }
.LBB0_604:
	v_add_u32_e32 v3, s0, v196
	v_ashrrev_i32_e32 v5, 5, v3
	v_ashrrev_i32_e32 v4, 9, v3
	v_add_u32_e32 v3, 0x200, v3
	v_and_or_b32 v5, v5, s1, v1
	v_lshlrev_b32_e32 v6, 6, v4
	v_lshlrev_b32_e32 v7, 10, v4
	v_ashrrev_i32_e32 v8, 9, v3
	v_ashrrev_i32_e32 v3, 5, v3
	v_mad_u64_u32 v[4:5], s[6:7], v5, s4, v[0:1]
	v_and_b32_e32 v5, 0xc0, v6
	v_and_or_b32 v3, v3, s1, v1
	v_lshlrev_b32_e32 v6, 6, v8
	v_or3_b32 v12, v7, v2, v197
	v_lshlrev_b32_e32 v7, 10, v8
	v_add3_u32 v8, v4, v5, v200
	v_mad_u64_u32 v[4:5], s[6:7], v3, s4, v[0:1]
	v_and_b32_e32 v3, 0xc0, v6
	v_or3_b32 v14, v7, v2, v197
	v_add3_u32 v3, v4, v3, v200
	ds_read_b128 v[4:7], v8
	ds_read_b128 v[8:11], v3
	s_addk_i32 s0, 0x400
	v_ashrrev_i32_e32 v13, 31, v12
	s_cmpk_lg_i32 s0, 0x1000
	v_lshl_add_u64 v[12:13], v[12:13], 4, s[16:17]
	v_ashrrev_i32_e32 v15, 31, v14
	v_lshl_add_u64 v[14:15], v[14:15], 4, s[16:17]
	s_waitcnt lgkmcnt(1)
	global_store_dwordx4 v[12:13], v[4:7], off
	s_waitcnt lgkmcnt(0)
	global_store_dwordx4 v[14:15], v[8:11], off
	s_cbranch_scc1 .LBB0_604
	s_and_b64 vcc, exec, s[8:9]
	s_barrier
	s_cbranch_vccnz .LBB0_617
	s_lshl_b32 s0, s18, 1
	s_or_b32 s10, s0, s34
	s_cmpk_gt_i32 s10, 0x27f
	s_cbranch_scc1 .LBB0_617
	v_ashrrev_i32_e32 v14, 4, v224
	v_lshlrev_b32_e32 v20, 2, v224
	v_and_b32_e32 v20, 60, v20
	v_lshlrev_b32_e32 v30, 12, v14
	v_lshl_add_u32 v30, v20, 2, v30
	v_add_u32_e32 v31, 0x20000, v30
	s_and_b32 s4, s10, 15
	s_lshl_b32 s4, s4, 6
	s_lshr_b32 s5, s10, 4
	s_lshl_b32 s5, s5, 6
	s_and_b32 s6, s10, 7
	s_lshl_b32 s6, s6, 6
	s_lshr_b32 s7, s10, 3
	s_lshl_b32 s7, s7, 6
	s_lshl_b32 s8, s4, 12
	s_lshl_b32 s9, s5, 2
	s_add_u32 s8, s8, s9
	s_lshl_b32 s9, s6, 12
	s_lshl_b32 s11, s7, 2
	s_add_u32 s9, s9, s11
	v_readlane_b32 s42, v254, 14
	v_readlane_b32 s43, v254, 15
	v_readlane_b32 s44, v254, 18
	v_readlane_b32 s45, v254, 19
	v_readlane_b32 s46, v254, 16
	v_readlane_b32 s47, v254, 17
	s_add_u32 s42, s42, s8
	s_addc_u32 s43, s43, 0
	s_add_u32 s44, s44, s8
	s_addc_u32 s45, s45, 0
	s_add_u32 s46, s46, s9
	s_addc_u32 s47, s47, 0
	global_load_dwordx4 v[128:131], v30, s[42:43] nt
	global_load_dwordx4 v[132:135], v31, s[42:43] nt
	global_load_dwordx4 v[136:139], v30, s[42:43] offset:2048 nt
	global_load_dwordx4 v[140:143], v31, s[42:43] offset:2048 nt
	global_load_dwordx4 v[144:147], v30, s[44:45] nt
	global_load_dwordx4 v[148:151], v31, s[44:45] nt
	global_load_dwordx4 v[152:155], v30, s[44:45] offset:2048 nt
	global_load_dwordx4 v[156:159], v31, s[44:45] offset:2048 nt
	global_load_dwordx4 v[160:163], v30, s[46:47] nt
	global_load_dwordx4 v[164:167], v31, s[46:47] nt
	v_ashrrev_i32_e32 v16, 3, v224
	v_lshlrev_b32_e32 v9, 3, v224
	v_and_b32_e32 v9, 56, v9
	s_movk_i32 s16, 0x104
	v_mul_lo_u32 v10, v14, s16
	v_lshl_add_u32 v15, v20, 2, v10
	v_add_u32_e32 v17, 0x2080, v15
	v_mul_u32_u24_e32 v21, 0x104, v9
	v_lshl_add_u32 v19, v16, 2, v21
	v_add_u32_e32 v18, 0x400, v19
	v_add_u32_e32 v26, 0x4200, v15
	v_add_u32_e32 v27, 0x4200, v17
	v_add_u32_e32 v28, 0x4200, v19
	v_add_u32_e32 v29, 0x4200, v18
	v_lshlrev_b32_e32 v12, 11, v16
	v_lshl_add_u32 v12, v9, 1, v12
	v_lshlrev_b32_e32 v13, 10, v16
	v_lshl_add_u32 v13, v9, 1, v13
	s_lshl_b32 s8, s5, 11
	s_lshl_b32 s9, s4, 1
	s_add_u32 s8, s8, s9
	s_add_u32 s8, s8, 0x2400000
	s_add_u32 s48, s70, s8
	s_addc_u32 s49, s71, 0
	s_add_u32 s50, s48, 0x100000
	s_addc_u32 s51, s49, 0
	s_add_u32 s52, s48, 0x300000
	s_addc_u32 s53, s49, 0
	s_add_u32 s54, s48, 0x400000
	s_addc_u32 s55, s49, 0
	s_lshl_b32 s8, s7, 10
	s_lshl_b32 s9, s6, 1
	s_add_u32 s8, s8, s9
	s_add_u32 s8, s8, 0x2600000
	s_add_u32 s24, s70, s8
	s_addc_u32 s25, s71, 0
	s_waitcnt vmcnt(8)
	ds_write2_b32 v15, v128, v129 offset1:1
	ds_write2_b32 v15, v130, v131 offset0:2 offset1:3
	ds_write2_b32 v17, v132, v133 offset1:1
	ds_write2_b32 v17, v134, v135 offset0:2 offset1:3
	s_waitcnt lgkmcnt(0)
	s_barrier
	ds_read2_b32 v[0:1], v19 offset1:65
	ds_read2_b32 v[4:5], v19 offset0:130 offset1:195
	ds_read2_b32 v[6:7], v18 offset0:4 offset1:69
	ds_read2_b32 v[32:33], v18 offset0:134 offset1:199
	s_waitcnt lgkmcnt(0)
	v_cvt_pk_bf16_f32 v40, v0, v1
	v_cvt_pk_bf16_f32 v41, v4, v5
	v_cvt_pk_bf16_f32 v42, v6, v7
	v_cvt_pk_bf16_f32 v43, v32, v33
	global_store_dwordx4 v12, v[40:43], s[48:49]
	s_waitcnt vmcnt(7)
	ds_write2_b32 v26, v136, v137 offset1:1
	ds_write2_b32 v26, v138, v139 offset0:2 offset1:3
	ds_write2_b32 v27, v140, v141 offset1:1
	ds_write2_b32 v27, v142, v143 offset0:2 offset1:3
	s_waitcnt lgkmcnt(0)
	s_barrier
	ds_read2_b32 v[0:1], v28 offset1:65
	ds_read2_b32 v[4:5], v28 offset0:130 offset1:195
	ds_read2_b32 v[6:7], v29 offset0:4 offset1:69
	ds_read2_b32 v[32:33], v29 offset0:134 offset1:199
	s_waitcnt lgkmcnt(0)
	v_cvt_pk_bf16_f32 v44, v0, v1
	v_cvt_pk_bf16_f32 v45, v4, v5
	v_cvt_pk_bf16_f32 v46, v6, v7
	v_cvt_pk_bf16_f32 v47, v32, v33
	global_store_dwordx4 v12, v[44:47], s[50:51]
	s_waitcnt vmcnt(6)
	ds_write2_b32 v15, v144, v145 offset1:1
	ds_write2_b32 v15, v146, v147 offset0:2 offset1:3
	ds_write2_b32 v17, v148, v149 offset1:1
	ds_write2_b32 v17, v150, v151 offset0:2 offset1:3
	s_waitcnt lgkmcnt(0)
	s_barrier
	ds_read2_b32 v[0:1], v19 offset1:65
	ds_read2_b32 v[4:5], v19 offset0:130 offset1:195
	ds_read2_b32 v[6:7], v18 offset0:4 offset1:69
	ds_read2_b32 v[32:33], v18 offset0:134 offset1:199
	s_waitcnt lgkmcnt(0)
	v_cvt_pk_bf16_f32 v40, v0, v1
	v_cvt_pk_bf16_f32 v41, v4, v5
	v_cvt_pk_bf16_f32 v42, v6, v7
	v_cvt_pk_bf16_f32 v43, v32, v33
	global_store_dwordx4 v12, v[40:43], s[52:53]
	s_waitcnt vmcnt(5)
	ds_write2_b32 v26, v152, v153 offset1:1
	ds_write2_b32 v26, v154, v155 offset0:2 offset1:3
	ds_write2_b32 v27, v156, v157 offset1:1
	ds_write2_b32 v27, v158, v159 offset0:2 offset1:3
	s_waitcnt lgkmcnt(0)
	s_barrier
	ds_read2_b32 v[0:1], v28 offset1:65
	ds_read2_b32 v[4:5], v28 offset0:130 offset1:195
	ds_read2_b32 v[6:7], v29 offset0:4 offset1:69
	ds_read2_b32 v[32:33], v29 offset0:134 offset1:199
	s_waitcnt lgkmcnt(0)
	v_cvt_pk_bf16_f32 v44, v0, v1
	v_cvt_pk_bf16_f32 v45, v4, v5
	v_cvt_pk_bf16_f32 v46, v6, v7
	v_cvt_pk_bf16_f32 v47, v32, v33
	global_store_dwordx4 v12, v[44:47], s[54:55]
	s_waitcnt vmcnt(4)
	ds_write2_b32 v15, v160, v161 offset1:1
	ds_write2_b32 v15, v162, v163 offset0:2 offset1:3
	ds_write2_b32 v17, v164, v165 offset1:1
	ds_write2_b32 v17, v166, v167 offset0:2 offset1:3
	s_waitcnt lgkmcnt(0)
	s_barrier
	ds_read2_b32 v[0:1], v19 offset1:65
	ds_read2_b32 v[4:5], v19 offset0:130 offset1:195
	ds_read2_b32 v[6:7], v18 offset0:4 offset1:69
	ds_read2_b32 v[32:33], v18 offset0:134 offset1:199
	s_waitcnt lgkmcnt(0)
	v_cvt_pk_bf16_f32 v40, v0, v1
	v_cvt_pk_bf16_f32 v41, v4, v5
	v_cvt_pk_bf16_f32 v42, v6, v7
	v_cvt_pk_bf16_f32 v43, v32, v33
	global_store_dwordx4 v13, v[40:43], s[24:25]
	s_barrier

; #define PG8_STAGE(bufoff, gbase, voff) do { _Pragma("unroll") for (int _i = 0; _i < 2; ++_i) \
;         __builtin_amdgcn_global_load_lds((const unsigned*)((const char*)(gbase) + (voff)[_i]), (LAS unsigned*)(lds + (bufoff) + ldsw + _i * 8192), 16, 0, 0); } while (0)
; #define PG8_WAIT_V(n) asm volatile("s_waitcnt vmcnt(" #n ")" ::: "memory")
; #define PG8_BAR __builtin_amdgcn_s_barrier()
; template <class Epi, class Sched, bool ZERO>
; __device__ __forceinline__ void gemm_phase_acc(LAS unsigned char* lds, const Gemm g, const Sched& S, const Epi& E, f32x4 (&acc)[2][2][4][2]) {
;     ...
;     if constexpr (ZERO) {
; #pragma unroll
;     for (int a = 0; a < 2; ++a)
; #pragma unroll
;         for (int b = 0; b < 2; ++b)
; #pragma unroll
;             for (int m = 0; m < 4; ++m)
; #pragma unroll
;                 for (int n = 0; n < 2; ++n) acc[a][b][m][n] = (f32x4){0.f, 0.f, 0.f, 0.f};
;     }
;     ...
;     PG8_STAGE(PG8_SB(0, 0), cB, voffB); PG8_STAGE(PG8_SA(0, 0), cA, voffA); PG8_STAGE(PG8_SB(0, 1), cB + hstep, voffB); PG8_STAGE(PG8_SA(0, 1), cA + hstep, voffA);
;     if (wr == 1) PG8_BAR;
;     PG8_WAIT_V(4); PG8_BAR;
;     PG8_STAGE(PG8_SB(1, 0), cB + kstep, voffB); PG8_STAGE(PG8_SA(1, 0), cA + kstep, voffA); PG8_STAGE(PG8_SB(1, 1), cB + hstep + kstep, voffB);
;     PG8_WAIT_V(6); PG8_BAR;
.LBB0_630:
	v_and_b32_e32 v15, 15, v13
	v_bfe_u32 v16, v13, 4, 2
	s_and_b32 s17, s3, 3
	v_lshl_or_b32 v85, s4, 6, v15
	v_lshlrev_b32_e32 v84, 4, v16
	s_lshl_b32 s3, s4, 13
	v_lshlrev_b32_e32 v13, 2, v13
	s_mov_b64 s[4:5], 0x80
	v_lshl_or_b32 v15, v15, 6, v84
	v_and_b32_e32 v13, 32, v13
	s_add_i32 m0, s11, 0x18000
	v_lshl_add_u64 v[6:7], v[6:7], 0, s[4:5]
	v_bitop3_b32 v16, v15, s3, v13 bitop3:0xde
	s_lshl_b32 s3, s17, 12
	s_waitcnt vmcnt(4)
	s_barrier
	global_load_lds_dwordx4 v[6:7], off
	v_lshl_add_u64 v[4:5], v[4:5], 0, s[4:5]
	s_add_i32 m0, s11, 0x1a000
	s_add_i32 s24, s11, 0x8000
	s_add_i32 s25, s11, 0xa000
	global_load_lds_dwordx4 v[4:5], off
	v_lshl_add_u64 v[2:3], v[2:3], 0, s[4:5]
	s_mov_b32 m0, s24
	s_add_u32 s26, s0, 0x40080
	global_load_lds_dwordx4 v[2:3], off
	v_lshl_add_u64 v[0:1], v[0:1], 0, s[4:5]
	s_mov_b32 m0, s25
	s_addc_u32 s27, s1, 0
	global_load_lds_dwordx4 v[0:1], off
	s_add_i32 m0, s11, 0x1c000
	v_lshl_add_u64 v[0:1], s[26:27], 0, v[50:51]
	global_load_lds_dwordx4 v[0:1], off
	v_lshl_add_u64 v[0:1], s[26:27], 0, v[62:63]
	s_add_i32 m0, s11, 0x1e000
	v_readlane_b32 s26, v254, 26
	global_load_lds_dwordx4 v[0:1], off
	v_lshlrev_b32_e32 v0, 14, v8
	v_and_b32_e32 v0, 0xffff8000, v0
	v_lshl_add_u32 v0, v9, 11, v0
	v_and_b32_e32 v1, 1, v8
	v_lshl_or_b32 v0, v1, 6, v0
	v_readlane_b32 s27, v254, 27
	s_add_u32 s26, s70, s26
	v_lshl_add_u32 v0, v10, 1, v0
	v_mov_b32_e32 v1, v51
	s_addc_u32 s27, s71, s27
	s_mov_b64 s[8:9], 0x40080
	v_lshl_add_u64 v[0:1], s[26:27], 0, v[0:1]
	v_lshl_add_u64 v[72:73], v[0:1], 0, s[8:9]
	v_lshlrev_b32_e32 v0, 14, v11
	v_and_b32_e32 v0, 0xffff8000, v0
	s_lshl_b32 s2, s2, 16
	v_lshl_add_u32 v0, v12, 11, v0
	v_and_b32_e32 v1, 1, v11
	s_and_b32 s2, s2, 0x180000
	v_lshl_or_b32 v0, v1, 6, v0
	s_add_u32 s2, s70, s2
	v_bitop3_b32 v13, v15, s3, v13 bitop3:0xde
	v_lshl_add_u32 v0, v14, 1, v0
	v_mov_b32_e32 v1, v51
	s_addc_u32 s3, s71, 0
	s_waitcnt vmcnt(6)
	v_lshl_add_u64 v[0:1], s[26:27], 0, v[0:1]
	s_add_u32 s26, s2, 0x2e00100
	s_addc_u32 s27, s3, 0
	s_add_i32 s31, s35, s6
	s_add_i32 s39, s22, s6
	s_add_i32 s41, s23, s6
	s_add_i32 s43, s33, s6
	v_lshl_add_u64 v[74:75], v[0:1], 0, s[8:9]
	s_mov_b32 s28, -2
	s_mov_b64 s[2:3], 0
	v_add_u32_e32 v86, s35, v13
	v_add_u32_e32 v87, 0, v16
	s_add_i32 s29, s11, 0xc000
	s_add_i32 s30, s11, 0xe000
	v_add_u32_e32 v88, s22, v13
	s_add_i32 s38, s31, 0x2000
	s_add_i32 s40, s39, 0x2000
	v_add_u32_e32 v89, s23, v13
	v_add_u32_e32 v90, s33, v13
	s_add_i32 s42, s41, 0x2000
	s_add_i32 s44, s43, 0x2000
	v_mov_b32_e32 v0, v51
	v_mov_b32_e32 v1, v51
	v_mov_b32_e32 v2, v51
	v_mov_b32_e32 v3, v51
	v_mov_b32_e32 v4, v51
	v_mov_b32_e32 v5, v51
	v_mov_b32_e32 v6, v51
	v_mov_b32_e32 v7, v51
	v_mov_b32_e32 v16, v51
	v_mov_b32_e32 v17, v51
	v_mov_b32_e32 v18, v51
	v_mov_b32_e32 v19, v51
	v_mov_b32_e32 v20, v51
	v_mov_b32_e32 v21, v51
	v_mov_b32_e32 v22, v51
	v_mov_b32_e32 v23, v51
	v_mov_b32_e32 v32, v51
	v_mov_b32_e32 v33, v51
	v_mov_b32_e32 v34, v51
	v_mov_b32_e32 v35, v51
	v_mov_b32_e32 v36, v51
	v_mov_b32_e32 v37, v51
	v_mov_b32_e32 v38, v51
	v_mov_b32_e32 v39, v51
	v_mov_b32_e32 v52, v51
	v_mov_b32_e32 v53, v51
	v_mov_b32_e32 v54, v51
	v_mov_b32_e32 v55, v51
	v_mov_b32_e32 v56, v51
	v_mov_b32_e32 v57, v51
	v_mov_b32_e32 v58, v51
	v_mov_b32_e32 v59, v51
	v_mov_b32_e32 v8, v51
	v_mov_b32_e32 v9, v51
	v_mov_b32_e32 v10, v51
	v_mov_b32_e32 v11, v51
	v_mov_b32_e32 v12, v51
	v_mov_b32_e32 v13, v51
	v_mov_b32_e32 v14, v51
	v_mov_b32_e32 v15, v51
	v_mov_b32_e32 v24, v51
	v_mov_b32_e32 v25, v51
	v_mov_b32_e32 v26, v51
	v_mov_b32_e32 v27, v51
	v_mov_b32_e32 v28, v51
	v_mov_b32_e32 v29, v51
	v_mov_b32_e32 v30, v51
	v_mov_b32_e32 v31, v51
	v_mov_b32_e32 v40, v51
	v_mov_b32_e32 v41, v51
	v_mov_b32_e32 v42, v51
	v_mov_b32_e32 v43, v51
	v_mov_b32_e32 v44, v51
	v_mov_b32_e32 v45, v51
	v_mov_b32_e32 v46, v51
	v_mov_b32_e32 v47, v51
	v_mov_b32_e32 v64, v51
	v_mov_b32_e32 v65, v51
	v_mov_b32_e32 v66, v51
	v_mov_b32_e32 v67, v51
	v_mov_b32_e32 v68, v51
	v_mov_b32_e32 v69, v51
	v_mov_b32_e32 v70, v51
	v_mov_b32_e32 v71, v51
	v_mov_b32_e32 v76, v51
	v_mov_b32_e32 v77, v51
	v_mov_b32_e32 v78, v51
	v_mov_b32_e32 v79, v51
	v_mov_b32_e32 v80, v51
	v_mov_b32_e32 v81, v51
	v_mov_b32_e32 v82, v51
	v_mov_b32_e32 v83, v51
	v_mov_b32_e32 v104, v51
	v_mov_b32_e32 v105, v51
	v_mov_b32_e32 v106, v51
	v_mov_b32_e32 v107, v51
	v_mov_b32_e32 v108, v51
	v_mov_b32_e32 v109, v51
	v_mov_b32_e32 v110, v51
	v_mov_b32_e32 v111, v51
	v_mov_b32_e32 v128, v51
	v_mov_b32_e32 v129, v51
	v_mov_b32_e32 v130, v51
	v_mov_b32_e32 v131, v51
	v_mov_b32_e32 v132, v51
	v_mov_b32_e32 v133, v51
	v_mov_b32_e32 v134, v51
	v_mov_b32_e32 v135, v51
	v_mov_b32_e32 v144, v51
	v_mov_b32_e32 v145, v51
	v_mov_b32_e32 v146, v51
	v_mov_b32_e32 v147, v51
	v_mov_b32_e32 v148, v51
	v_mov_b32_e32 v149, v51
	v_mov_b32_e32 v150, v51
	v_mov_b32_e32 v151, v51
	v_mov_b32_e32 v92, v51
	v_mov_b32_e32 v93, v51
	v_mov_b32_e32 v94, v51
	v_mov_b32_e32 v95, v51
	v_mov_b32_e32 v96, v51
	v_mov_b32_e32 v97, v51
	v_mov_b32_e32 v98, v51
	v_mov_b32_e32 v99, v51
	v_mov_b32_e32 v116, v51
	v_mov_b32_e32 v117, v51
	v_mov_b32_e32 v118, v51
	v_mov_b32_e32 v119, v51
	v_mov_b32_e32 v120, v51
	v_mov_b32_e32 v121, v51
	v_mov_b32_e32 v122, v51
	v_mov_b32_e32 v123, v51
	v_mov_b32_e32 v136, v51
	v_mov_b32_e32 v137, v51
	v_mov_b32_e32 v138, v51
	v_mov_b32_e32 v139, v51
	v_mov_b32_e32 v140, v51
	v_mov_b32_e32 v141, v51
	v_mov_b32_e32 v142, v51
	v_mov_b32_e32 v143, v51
	v_mov_b32_e32 v152, v51
	v_mov_b32_e32 v153, v51
	v_mov_b32_e32 v154, v51
	v_mov_b32_e32 v155, v51
	v_mov_b32_e32 v156, v51
	v_mov_b32_e32 v157, v51
	v_mov_b32_e32 v158, v51
	v_mov_b32_e32 v159, v51
	s_barrier
	s_nop 0
